# in_proj GEMM on 192 workgroups, 64 side workgroups start the decode stream during phase 3; phase 2->3 barrier blocking again
# speedup vs baseline: 1.0129x; 1.0047x over previous
.LBB0_249:
	v_and_b32_e32 v230, 48, v0
	v_sub_u32_e32 v230, 0, v230
	v_ashrrev_i32_e32 v231, 31, v230
	s_add_u32 s58, s68, 0x80000
	s_addc_u32 s59, s69, 0
	s_add_u32 s62, s68, 0x2500000
	s_addc_u32 s63, s69, 0
	s_add_u32 s0, s68, 0x2540000
	s_addc_u32 s1, s69, 0
	v_writelane_b32 v245, s0, 36
	s_nop 1
	v_writelane_b32 v245, s1, 37
	s_add_u32 s0, s68, 0x2580000
	s_addc_u32 s1, s69, 0
	v_writelane_b32 v245, s0, 38
	s_nop 1
	v_writelane_b32 v245, s1, 39
	s_add_u32 s0, s68, 0x8c00000
	s_addc_u32 s1, s69, 0
	v_writelane_b32 v245, s0, 40
	s_nop 1
	v_writelane_b32 v245, s1, 41
	s_add_u32 s0, s68, 0xa000000
	s_addc_u32 s1, s69, 0
	v_writelane_b32 v245, s0, 42
	s_nop 1
	v_writelane_b32 v245, s1, 43
	s_add_u32 s0, s68, 0xb400000
	s_addc_u32 s1, s69, 0
	v_writelane_b32 v245, s0, 44
	s_nop 1
	v_writelane_b32 v245, s1, 45
	s_add_u32 s0, s68, 0xc800000
	s_addc_u32 s1, s69, 0
	s_add_u32 s56, s68, 0xdc00000
	s_addc_u32 s57, s69, 0
	v_writelane_b32 v245, s0, 46
	s_cmp_lt_i32 s92, 4
	s_nop 0
	v_writelane_b32 v245, s1, 47
	s_cselect_b64 s[0:1], -1, 0
	s_cmp_gt_i32 s93, 3
	s_cselect_b64 s[2:3], -1, 0
	s_and_b64 s[0:1], s[0:1], s[2:3]
	s_andn2_b64 vcc, exec, s[0:1]
	s_cbranch_vccnz .LBB0_508
	s_movk_i32 s15, 0xc0
	s_cmp_ge_i32 s12, s15
	s_mov_b64 s[0:1], -1
	s_cbranch_scc0 .LBB0_326
	s_sub_i32 s0, s12, s15
	s_and_b32 s0, s0, -8
	s_and_b32 s1, s12, 7
	s_or_b32 s0, s0, s1
	s_addk_i32 s0, 0x80
	s_mul_i32 s2, s15, 3
	s_ashr_i32 s3, s0, 31
	s_mul_hi_i32 s1, s15, 3
	s_add_u32 s0, s2, s0
	s_addc_u32 s1, s1, s3
	s_waitcnt vmcnt(1)
	v_mov_b64_e32 v[2:3], 0x37f
	s_waitcnt vmcnt(0)
	v_mov_b32_e32 v13, v0
	v_cmp_gt_i64_e32 vcc, s[0:1], v[2:3]
	s_nop 0
	v_readfirstlane_b32 s6, v13
	s_branch .LBB0_325
	v_lshlrev_b32_e32 v1, 4, v13
	v_add_u32_e32 v2, 0x2000, v1
	v_ashrrev_i32_e32 v3, 31, v2
	v_lshrrev_b32_e32 v3, 22, v3
	v_add_u32_e32 v3, v2, v3
	v_ashrrev_i32_e32 v10, 10, v3
	v_mul_i32_i24_e32 v3, 0x400, v10
	v_sub_u32_e32 v2, v2, v3
	v_lshrrev_b32_e32 v3, 4, v2
	v_bitop3_b32 v2, v3, v2, 32 bitop3:0x6c
	v_ashrrev_i32_e32 v3, 31, v2
	v_lshrrev_b32_e32 v3, 26, v3
	v_add_u32_e32 v3, v2, v3
	v_lshlrev_b32_e32 v4, 3, v10
	v_ashrrev_i32_e32 v11, 6, v3
	v_and_b32_e32 v4, -16, v4
	v_add_u32_e32 v4, v11, v4
	v_and_b32_e32 v5, 3, v11
	s_mov_b32 s1, 0x1fffe0
	v_lshrrev_b32_e32 v6, 2, v4
	v_lshlrev_b32_e32 v7, 1, v4
	v_and_b32_e32 v3, 0xc0, v3
	v_and_or_b32 v5, v4, s1, v5
	v_and_b32_e32 v6, 4, v6
	v_and_b32_e32 v7, 24, v7
	v_sub_u32_e32 v2, v2, v3
	v_mov_b32_e32 v3, 1
	v_or3_b32 v5, v5, v6, v7
	v_lshlrev_b32_e32 v6, 5, v10
	v_ashrrev_i16_sdwa v2, v3, sext(v2) dst_sel:DWORD dst_unused:UNUSED_PAD src0_sel:DWORD src1_sel:BYTE_0
	v_and_b32_e32 v6, 32, v6
	v_bfe_i32 v12, v2, 0, 16
	v_add_lshl_u32 v2, v6, v12, 1
	v_lshl_add_u32 v130, v5, 11, v2
	v_lshl_add_u32 v132, v4, 11, v2
	v_bfe_i32 v2, v13, 27, 1
	v_lshrrev_b32_e32 v2, 22, v2
	v_add_u32_e32 v2, v1, v2
	v_and_b32_e32 v2, 0xfffffc00, v2
	v_sub_u32_e32 v1, v1, v2
	v_lshrrev_b32_e32 v2, 4, v1
	v_ashrrev_i32_e32 v4, 31, v13
	v_bitop3_b32 v1, v2, v1, 32 bitop3:0x6c
	v_lshrrev_b32_e32 v4, 26, v4
	v_ashrrev_i32_e32 v2, 31, v1
	v_add_u32_e32 v4, v13, v4
	v_lshrrev_b32_e32 v2, 26, v2
	v_ashrrev_i32_e32 v15, 6, v4
	v_add_u32_e32 v2, v1, v2
	v_lshlrev_b32_e32 v4, 3, v15
	v_ashrrev_i32_e32 v14, 6, v2
	v_and_b32_e32 v4, -16, v4
	v_add_u32_e32 v4, v14, v4
	v_and_b32_e32 v5, 3, v14
	v_and_or_b32 v5, v4, s1, v5
	s_ashr_i32 s1, s0, 31
	s_lshr_b32 s1, s1, 29
	s_add_i32 s1, s0, s1
	s_ashr_i32 s17, s6, 6
	s_ashr_i32 s2, s1, 3
	s_and_b32 s1, s1, -8
	s_mov_b64 s[38:39], s[62:63]
	s_ashr_i32 s18, s6, 8
	s_lshl_b32 s62, s17, 10
	s_sub_i32 s0, s0, s1
	s_cmp_lt_i32 s0, 0
	s_movk_i32 s1, 0x71
	s_cselect_b32 s1, s1, 0x70
	s_mul_i32 s0, s0, s1
	s_add_i32 s0, s0, s2
	s_mul_hi_i32 s1, s0, 0x92492493
	s_add_i32 s1, s1, s0
	s_lshr_b32 s2, s1, 31
	s_ashr_i32 s1, s1, 6
	s_add_i32 s1, s1, s2
	s_lshl_b32 s2, s1, 3
	v_and_b32_e32 v2, 0xc0, v2
	s_sub_i32 s3, 64, s2
	v_sub_u32_e32 v1, v1, v2
	s_min_i32 s3, s3, 8
	v_ashrrev_i16_sdwa v1, v3, sext(v1) dst_sel:DWORD dst_unused:UNUSED_PAD src0_sel:DWORD src1_sel:BYTE_0
	s_abs_i32 s4, s3
	v_bfe_i32 v16, v1, 0, 16
	v_cvt_f32_u32_e32 v1, s4
	s_sub_i32 s7, 0, s4
	s_mulk_i32 s1, 0x70
	s_sub_i32 s1, s0, s1
	v_rcp_iflag_f32_e32 v1, v1
	s_abs_i32 s5, s1
	s_xor_b32 s0, s1, s3
	s_ashr_i32 s0, s0, 31
	v_mul_f32_e32 v1, 0x4f7ffffe, v1
	v_cvt_u32_f32_e32 v1, v1
	v_lshrrev_b32_e32 v6, 2, v4
	v_lshlrev_b32_e32 v7, 1, v4
	v_and_b32_e32 v6, 4, v6
	v_readfirstlane_b32 s10, v1
	s_mul_i32 s7, s7, s10
	s_mul_hi_u32 s7, s10, s7
	s_add_i32 s10, s10, s7
	s_mul_hi_u32 s7, s5, s10
	s_mul_i32 s10, s7, s4
	s_sub_i32 s5, s5, s10
	s_add_i32 s10, s7, 1
	s_sub_i32 s11, s5, s4
	s_cmp_ge_u32 s5, s4
	s_cselect_b32 s7, s10, s7
	s_cselect_b32 s5, s11, s5
	s_add_i32 s10, s7, 1
	s_cmp_ge_u32 s5, s4
	s_cselect_b32 s4, s10, s7
	s_xor_b32 s4, s4, s0
	s_sub_i32 s0, s4, s0
	s_mul_i32 s3, s0, s3
	s_sub_i32 s1, s1, s3
	s_add_i32 s2, s2, s1
	v_and_b32_e32 v7, 24, v7
	s_ashr_i32 s3, s2, 31
	s_ashr_i32 s1, s0, 31
	v_or3_b32 v5, v5, v6, v7
	v_lshlrev_b32_e32 v6, 5, v15
	s_lshl_b64 s[74:75], s[2:3], 19
	s_lshl_b64 s[78:79], s[0:1], 19
	v_and_b32_e32 v6, 32, v6
	s_add_u32 s4, s8, s78
	v_add_lshl_u32 v2, v6, v16, 1
	s_addc_u32 s5, s9, s79
	s_add_i32 s1, s62, 0
	v_lshl_add_u32 v134, v5, 11, v2
	s_add_i32 m0, s1, 0x10000
	v_lshl_add_u32 v136, v4, 11, v2
	global_load_lds_dwordx4 v134, s[4:5]
	s_add_i32 m0, s1, 0x12000
	s_add_u32 s10, s4, 0x40000
	global_load_lds_dwordx4 v130, s[4:5]
	s_addc_u32 s11, s5, 0
	s_add_i32 m0, s1, 0x14000
	v_mov_b32_e32 v135, 0
	global_load_lds_dwordx4 v134, s[10:11]
	s_add_i32 m0, s1, 0x16000
	v_mov_b32_e32 v131, v135
	global_load_lds_dwordx4 v130, s[10:11]
	s_add_u32 s10, s52, s74
	s_addc_u32 s11, s53, s75
	s_add_i32 s7, s1, 0x2000
	s_mov_b32 m0, s1
	s_add_u32 s24, s10, 0x40000
	global_load_lds_dwordx4 v136, s[10:11]
	s_mov_b32 m0, s7
	s_addc_u32 s25, s11, 0
	s_add_i32 s13, s1, 0x4000
	global_load_lds_dwordx4 v132, s[10:11]
	s_mov_b32 m0, s13
	s_add_i32 s16, s1, 0x6000
	global_load_lds_dwordx4 v136, s[24:25]
	s_mov_b32 m0, s16
	v_mov_b32_e32 v137, v135
	global_load_lds_dwordx4 v132, s[24:25]
	v_mov_b32_e32 v133, v135
	s_mov_b64 s[36:37], s[84:85]
	v_lshl_add_u64 v[8:9], s[4:5], 0, v[134:135]
	v_lshl_add_u64 v[6:7], s[4:5], 0, v[130:131]
	v_lshl_add_u64 v[4:5], s[10:11], 0, v[136:137]
	s_cmp_lg_u32 s18, 1
	v_lshl_add_u64 v[2:3], s[10:11], 0, v[132:133]
	s_cbranch_scc1 .LBB0_254
	s_barrier

.LBB0_332:
	v_lshrrev_b32_e32 v18, 1, v16
	s_and_b32 s1, s12, 0xffffffe0
	v_and_b32_e32 v18, 24, v18
	s_cmpk_eq_i32 s1, 0x80
	v_and_b32_e32 v17, 15, v16
	v_lshlrev_b32_e32 v19, 1, v18
	v_lshlrev_b32_e32 v16, 2, v16
	s_mov_b64 s[74:75], 0
	v_lshl_or_b32 v19, v17, 6, v19
	s_lshl_b32 s1, s2, 13
	v_and_b32_e32 v16, 32, v16
	v_bitop3_b32 v20, v19, s1, v16 bitop3:0xde
	s_lshl_b32 s1, s3, 5
	s_mov_b64 s[88:89], 0x80
	s_and_b32 s1, s1, 0x60
	s_add_i32 m0, s60, 0x18000
	v_lshl_add_u64 v[8:9], v[8:9], 0, s[88:89]
	s_ashr_i32 s62, s15, 31
	s_ashr_i32 s63, s12, 31
	v_lshl_or_b32 v1, s2, 6, v17
	s_lshl_b32 s2, s1, 7
	s_waitcnt vmcnt(2)
	s_barrier
	global_load_lds_dwordx4 v[8:9], off
	v_lshl_add_u64 v[6:7], v[6:7], 0, s[88:89]
	s_add_i32 m0, s60, 0x1a000
	s_add_i32 s13, s60, 0x8000
	s_add_i32 s6, s60, 0xa000
	v_bitop3_b32 v168, v19, s2, v16 bitop3:0xde
	global_load_lds_dwordx4 v[6:7], off
	v_lshl_add_u64 v[2:3], v[2:3], 0, s[88:89]
	s_mov_b32 m0, s13
	s_add_u32 s2, s84, 0x40080
	global_load_lds_dwordx4 v[2:3], off
	v_lshl_add_u64 v[2:3], v[4:5], 0, s[88:89]
	s_mov_b32 m0, s6
	s_addc_u32 s3, s85, 0
	global_load_lds_dwordx4 v[2:3], off
	s_add_i32 m0, s60, 0x1c000
	v_lshl_add_u64 v[2:3], s[2:3], 0, v[140:141]
	global_load_lds_dwordx4 v[2:3], off
	v_lshl_add_u64 v[2:3], s[2:3], 0, v[144:145]
	s_add_i32 m0, s60, 0x1e000
	s_cmpk_lt_u32 s7, 0x100
	global_load_lds_dwordx4 v[2:3], off
	v_lshlrev_b32_e32 v2, 14, v10
	v_and_b32_e32 v2, 0xffff8000, v2
	v_lshl_add_u32 v2, v11, 11, v2
	v_and_b32_e32 v3, 1, v10
	v_lshl_or_b32 v2, v3, 6, v2
	v_lshl_add_u32 v148, v12, 1, v2
	v_lshlrev_b32_e32 v2, 14, v13
	v_and_b32_e32 v2, 0xffff8000, v2
	v_lshl_add_u32 v2, v14, 11, v2
	v_and_b32_e32 v3, 1, v13
	s_waitcnt vmcnt(6)
	v_lshl_or_b32 v2, v3, 6, v2
	s_cselect_b64 s[90:91], -1, 0
	v_lshl_add_u32 v150, v15, 1, v2
	s_add_i32 s7, 0, 0x10000
	s_add_i32 s16, 0, 0x14000
	v_mbcnt_lo_u32_b32 v2, -1, 0
	s_movk_i32 s77, 0x80
	v_cmp_eq_u32_e64 s[2:3], 0, v17
	v_or_b32_e32 v169, s1, v18
	v_mov_b32_e32 v149, v147
	v_mov_b32_e32 v151, v147
	v_add_u32_e32 v170, s7, v168
	v_add_u32_e32 v171, s16, v168
	v_add_u32_e32 v172, 0, v20
	v_mov_b64_e32 v[152:153], 0x37f
	v_mov_b32_e32 v173, 0x3db504f3
	v_mov_b32_e32 v174, 0x3e38aa3b
	v_mbcnt_hi_u32_b32 v175, -1, v2
	s_barrier
	s_branch .LBB0_335

.LBB0_412:
	s_cmp_ge_i32 s12, s15
	s_cselect_b64 s[72:73], -1, 0
	s_cmp_lt_u32 s90, 64
	s_cselect_b64 s[0:1], -1, 0
	s_and_b64 s[0:1], s[72:73], s[0:1]
	s_cmpk_lt_i32 s12, 0xe0
	s_cselect_b64 s[2:3], -1, 0
	s_and_b64 s[0:1], s[0:1], s[2:3]
	s_andn2_b64 vcc, exec, s[0:1]
	s_cbranch_vccnz .LBB0_414
	s_sub_i32 s4, s12, s15
	s_and_b32 s0, s4, 3
	s_lshr_b32 s8, s4, 2
	s_lshl_b32 s0, s0, 2
	s_mov_b32 s9, 0
	s_add_u32 s0, s86, s0
	s_addc_u32 s1, s87, 0
	s_lshl_b64 s[2:3], s[8:9], 16
	s_waitcnt vmcnt(0)
	v_lshl_or_b32 v2, v214, 10, s2
	s_waitcnt lgkmcnt(0)
	v_mov_b32_e32 v3, s3
	v_lshl_add_u64 v[34:35], s[0:1], 0, v[2:3]
	global_load_dword v1, v[34:35], off offset:16
	global_load_dword v36, v[34:35], off offset:48
	global_load_dword v37, v[34:35], off offset:80
	global_load_dword v38, v[34:35], off offset:112
	global_load_dword v39, v[34:35], off offset:144
	global_load_dword v40, v[34:35], off offset:176
	global_load_dword v41, v[34:35], off offset:208
	global_load_dword v42, v[34:35], off offset:240
	global_load_dword v43, v[34:35], off offset:272
	global_load_dword v44, v[34:35], off offset:304
	global_load_dword v45, v[34:35], off offset:336
	global_load_dword v46, v[34:35], off offset:368
	global_load_dword v47, v[34:35], off offset:400
	global_load_dword v48, v[34:35], off offset:432
	global_load_dword v49, v[34:35], off offset:464
	global_load_dword v50, v[34:35], off offset:496
	global_load_dword v51, v[34:35], off offset:528
	global_load_dword v52, v[34:35], off offset:560
	global_load_dword v53, v[34:35], off offset:592
	global_load_dword v54, v[34:35], off offset:624
	global_load_dword v55, v[34:35], off offset:656
	global_load_dword v56, v[34:35], off offset:688
	global_load_dword v57, v[34:35], off offset:720
	global_load_dword v58, v[34:35], off offset:752
	global_load_dword v59, v[34:35], off offset:784
	global_load_dword v60, v[34:35], off offset:816
	global_load_dword v61, v[34:35], off offset:848
	global_load_dword v62, v[34:35], off offset:880
	global_load_dword v63, v[34:35], off offset:912
	global_load_dword v64, v[34:35], off offset:944
	global_load_dword v65, v[34:35], off offset:976
	global_load_dword v66, v[34:35], off offset:1008
	global_load_dword v27, v[34:35], off offset:96
	global_load_dword v26, v[34:35], off offset:64
	global_load_dword v33, v[34:35], off offset:32
	global_load_dword v32, v[34:35], off
	global_load_dword v23, v[34:35], off offset:224
	global_load_dword v22, v[34:35], off offset:192
	global_load_dword v31, v[34:35], off offset:160
	global_load_dword v30, v[34:35], off offset:128
	global_load_dword v19, v[34:35], off offset:352
	global_load_dword v18, v[34:35], off offset:320
	global_load_dword v29, v[34:35], off offset:288
	global_load_dword v28, v[34:35], off offset:256
	global_load_dword v15, v[34:35], off offset:480
	global_load_dword v14, v[34:35], off offset:448
	global_load_dword v25, v[34:35], off offset:416
	global_load_dword v24, v[34:35], off offset:384
	global_load_dword v11, v[34:35], off offset:608
	global_load_dword v10, v[34:35], off offset:576
	global_load_dword v21, v[34:35], off offset:544
	global_load_dword v20, v[34:35], off offset:512
	global_load_dword v7, v[34:35], off offset:736
	global_load_dword v6, v[34:35], off offset:704
	global_load_dword v17, v[34:35], off offset:672
	global_load_dword v16, v[34:35], off offset:640
	global_load_dword v3, v[34:35], off offset:864
	global_load_dword v2, v[34:35], off offset:832
	global_load_dword v13, v[34:35], off offset:800
	global_load_dword v12, v[34:35], off offset:768
	global_load_dword v5, v[34:35], off offset:992
	global_load_dword v4, v[34:35], off offset:960
	global_load_dword v9, v[34:35], off offset:928
	global_load_dword v8, v[34:35], off offset:896
	v_mbcnt_lo_u32_b32 v34, -1, 0
	v_mbcnt_hi_u32_b32 v67, -1, v34
	v_and_b32_e32 v68, 64, v67
	v_add_u32_e32 v34, -1, v67
	v_cmp_lt_i32_e32 vcc, v34, v68
	v_add_u32_e32 v69, -8, v67
	s_mov_b32 s5, s9
	v_cndmask_b32_e32 v34, v34, v67, vcc
	v_lshlrev_b32_e32 v120, 2, v34
	v_add_u32_e32 v34, -2, v67
	v_cmp_lt_i32_e32 vcc, v34, v68
	s_lshl_b64 s[4:5], s[4:5], 13
	v_cmp_gt_u32_e64 s[8:9], 16, v214
	v_cndmask_b32_e32 v34, v34, v67, vcc
	v_lshlrev_b32_e32 v83, 2, v34
	v_add_u32_e32 v34, -4, v67
	v_cmp_lt_i32_e32 vcc, v34, v68
	v_cmp_gt_u32_e64 s[10:11], 32, v214
	s_mov_b32 s6, 0xff800000
	v_cndmask_b32_e32 v34, v34, v67, vcc
	v_lshlrev_b32_e32 v102, 2, v34
	s_waitcnt vmcnt(62)
	v_add_f32_e32 v34, 0, v1
	v_add_f32_e32 v35, v34, v36
	s_waitcnt vmcnt(61)
	v_add_f32_e32 v36, v35, v37
	s_waitcnt vmcnt(60)
	v_add_f32_e32 v37, v36, v38
	s_waitcnt vmcnt(59)
	v_add_f32_e32 v38, v37, v39
	s_waitcnt vmcnt(58)
	v_add_f32_e32 v39, v38, v40
	s_waitcnt vmcnt(57)
	v_add_f32_e32 v40, v39, v41
	s_waitcnt vmcnt(56)
	v_add_f32_e32 v41, v40, v42
	s_waitcnt vmcnt(55)
	v_add_f32_e32 v42, v41, v43
	s_waitcnt vmcnt(54)
	v_add_f32_e32 v43, v42, v44
	s_waitcnt vmcnt(53)
	v_add_f32_e32 v44, v43, v45
	s_waitcnt vmcnt(52)
	v_add_f32_e32 v45, v44, v46
	s_waitcnt vmcnt(51)
	v_add_f32_e32 v46, v45, v47
	s_waitcnt vmcnt(50)
	v_add_f32_e32 v47, v46, v48
	s_waitcnt vmcnt(49)
	v_add_f32_e32 v48, v47, v49
	s_waitcnt vmcnt(48)
	v_add_f32_e32 v49, v48, v50
	s_waitcnt vmcnt(47)
	v_add_f32_e32 v50, v49, v51
	s_waitcnt vmcnt(46)
	v_add_f32_e32 v51, v50, v52
	s_waitcnt vmcnt(45)
	v_add_f32_e32 v52, v51, v53
	s_waitcnt vmcnt(44)
	v_add_f32_e32 v53, v52, v54
	s_waitcnt vmcnt(43)
	v_add_f32_e32 v54, v53, v55
	s_waitcnt vmcnt(42)
	v_add_f32_e32 v55, v54, v56
	s_waitcnt vmcnt(41)
	v_add_f32_e32 v56, v55, v57
	s_waitcnt vmcnt(40)
	v_add_f32_e32 v57, v56, v58
	s_waitcnt vmcnt(39)
	v_add_f32_e32 v58, v57, v59
	s_waitcnt vmcnt(38)
	v_add_f32_e32 v59, v58, v60
	s_waitcnt vmcnt(37)
	v_add_f32_e32 v60, v59, v61
	s_waitcnt vmcnt(36)
	v_add_f32_e32 v61, v60, v62
	s_waitcnt vmcnt(35)
	v_add_f32_e32 v62, v61, v63
	s_waitcnt vmcnt(34)
	v_add_f32_e32 v63, v62, v64
	s_waitcnt vmcnt(33)
	v_add_f32_e32 v64, v63, v65
	s_waitcnt vmcnt(32)
	v_add_f32_e32 v65, v64, v66
	ds_bpermute_b32 v1, v120, v65
	v_cmp_lt_i32_e32 vcc, v69, v68
	v_readlane_b32 s16, v245, 36
	v_readlane_b32 s18, v245, 38
	v_cndmask_b32_e32 v66, v69, v67, vcc
	s_waitcnt lgkmcnt(0)
	v_add_f32_e32 v1, v65, v1
	v_cmp_eq_u32_e32 vcc, 0, v214
	v_lshlrev_b32_e32 v106, 2, v66
	v_add_u32_e32 v66, -16, v67
	v_cndmask_b32_e32 v1, v1, v65, vcc
	ds_bpermute_b32 v69, v83, v1
	v_cmp_lt_i32_e64 s[0:1], v66, v68
	v_readlane_b32 s17, v245, 37
	v_readlane_b32 s19, v245, 39
	v_cndmask_b32_e64 v66, v66, v67, s[0:1]
	s_waitcnt lgkmcnt(0)
	v_add_f32_e32 v69, v1, v69
	v_cmp_gt_u32_e64 s[0:1], 2, v214
	v_lshlrev_b32_e32 v110, 2, v66
	v_subrev_u32_e32 v66, 32, v67
	v_cndmask_b32_e64 v1, v69, v1, s[0:1]
	ds_bpermute_b32 v69, v102, v1
	v_cmp_lt_i32_e64 s[2:3], v66, v68
	s_nop 1
	v_cndmask_b32_e64 v66, v66, v67, s[2:3]
	v_lshlrev_b32_e32 v114, 2, v66
	s_waitcnt lgkmcnt(0)
	v_add_f32_e32 v66, v1, v69
	v_cmp_gt_u32_e64 s[2:3], 4, v214
	v_mov_b32_e32 v67, s5
	v_mov_b32_e32 v81, v67
	v_cndmask_b32_e64 v1, v66, v1, s[2:3]
	ds_bpermute_b32 v72, v106, v1
	v_lshl_or_b32 v66, v214, 7, s4
	v_cmp_gt_u32_e64 s[4:5], 8, v214
	v_or_b32_e32 v80, 32, v66
	v_lshl_add_u64 v[68:69], s[62:63], 0, v[66:67]
	s_waitcnt lgkmcnt(0)
	v_add_f32_e32 v72, v1, v72
	v_cndmask_b32_e64 v1, v72, v1, s[4:5]
	ds_bpermute_b32 v78, v110, v1
	v_lshl_add_u64 v[70:71], s[16:17], 0, v[66:67]
	v_lshl_add_u64 v[72:73], s[18:19], 0, v[66:67]
	v_or_b32_e32 v74, 16, v66
	v_mov_b32_e32 v75, v67
	s_waitcnt lgkmcnt(0)
	v_add_f32_e32 v78, v1, v78
	v_cndmask_b32_e64 v1, v78, v1, s[8:9]
	ds_bpermute_b32 v82, v114, v1
	v_lshl_add_u64 v[76:77], s[62:63], 0, v[74:75]
	v_lshl_add_u64 v[78:79], s[16:17], 0, v[74:75]
	v_lshl_add_u64 v[74:75], s[18:19], 0, v[74:75]
	s_waitcnt lgkmcnt(0)
	v_add_f32_e32 v82, v1, v82
	v_cndmask_b32_e64 v1, v82, v1, s[10:11]
	v_sub_f32_e32 v82, v1, v65
	v_pk_add_f32 v[34:35], v[82:83], v[34:35] op_sel_hi:[0,1]
	s_waitcnt vmcnt(28)
	v_pk_add_f32 v[32:33], v[32:33], v[34:35] neg_lo:[0,1] neg_hi:[0,1]
	v_pk_add_f32 v[36:37], v[82:83], v[36:37] op_sel_hi:[0,1]
	v_max3_f32 v1, v32, s6, v33
	v_pk_add_f32 v[26:27], v[26:27], v[36:37] neg_lo:[0,1] neg_hi:[0,1]
	v_pk_add_f32 v[38:39], v[82:83], v[38:39] op_sel_hi:[0,1]
	v_max3_f32 v1, v1, v26, v27
	s_waitcnt vmcnt(24)
	v_pk_add_f32 v[30:31], v[30:31], v[38:39] neg_lo:[0,1] neg_hi:[0,1]
	v_pk_add_f32 v[40:41], v[82:83], v[40:41] op_sel_hi:[0,1]
	v_max3_f32 v1, v1, v30, v31
	v_pk_add_f32 v[84:85], v[22:23], v[40:41] neg_lo:[0,1] neg_hi:[0,1]
	v_pk_add_f32 v[42:43], v[82:83], v[42:43] op_sel_hi:[0,1]
	v_max3_f32 v1, v1, v84, v85
	s_waitcnt vmcnt(20)
	v_pk_add_f32 v[28:29], v[28:29], v[42:43] neg_lo:[0,1] neg_hi:[0,1]
	v_pk_add_f32 v[44:45], v[82:83], v[44:45] op_sel_hi:[0,1]
	v_max3_f32 v1, v1, v28, v29
	v_pk_add_f32 v[86:87], v[18:19], v[44:45] neg_lo:[0,1] neg_hi:[0,1]
	v_pk_add_f32 v[46:47], v[82:83], v[46:47] op_sel_hi:[0,1]
	v_max3_f32 v1, v1, v86, v87
	s_waitcnt vmcnt(16)
	v_pk_add_f32 v[88:89], v[24:25], v[46:47] neg_lo:[0,1] neg_hi:[0,1]
	v_pk_add_f32 v[48:49], v[82:83], v[48:49] op_sel_hi:[0,1]
	v_max3_f32 v1, v1, v88, v89
	v_pk_add_f32 v[90:91], v[14:15], v[48:49] neg_lo:[0,1] neg_hi:[0,1]
	v_pk_add_f32 v[50:51], v[82:83], v[50:51] op_sel_hi:[0,1]
	v_max3_f32 v1, v1, v90, v91
	s_waitcnt vmcnt(12)
	v_pk_add_f32 v[92:93], v[20:21], v[50:51] neg_lo:[0,1] neg_hi:[0,1]
	v_pk_add_f32 v[52:53], v[82:83], v[52:53] op_sel_hi:[0,1]
	v_max3_f32 v1, v1, v92, v93
	v_pk_add_f32 v[94:95], v[10:11], v[52:53] neg_lo:[0,1] neg_hi:[0,1]
	v_pk_add_f32 v[54:55], v[82:83], v[54:55] op_sel_hi:[0,1]
	v_max3_f32 v1, v1, v94, v95
	s_waitcnt vmcnt(8)
	v_pk_add_f32 v[96:97], v[16:17], v[54:55] neg_lo:[0,1] neg_hi:[0,1]
	v_pk_add_f32 v[56:57], v[82:83], v[56:57] op_sel_hi:[0,1]
	v_max3_f32 v1, v1, v96, v97
	v_pk_add_f32 v[98:99], v[6:7], v[56:57] neg_lo:[0,1] neg_hi:[0,1]
	v_pk_add_f32 v[14:15], v[82:83], v[58:59] op_sel_hi:[0,1]
	v_max3_f32 v1, v1, v98, v99
	s_waitcnt vmcnt(4)
	v_pk_add_f32 v[58:59], v[12:13], v[14:15] neg_lo:[0,1] neg_hi:[0,1]
	v_pk_add_f32 v[10:11], v[82:83], v[60:61] op_sel_hi:[0,1]
	v_max3_f32 v1, v1, v58, v59
	v_pk_add_f32 v[12:13], v[2:3], v[10:11] neg_lo:[0,1] neg_hi:[0,1]
	v_pk_add_f32 v[6:7], v[82:83], v[62:63] op_sel_hi:[0,1]
	v_max3_f32 v1, v1, v12, v13
	s_waitcnt vmcnt(0)
	v_pk_add_f32 v[8:9], v[8:9], v[6:7] neg_lo:[0,1] neg_hi:[0,1]
	v_pk_add_f32 v[2:3], v[82:83], v[64:65] op_sel_hi:[0,1]
	v_max3_f32 v1, v1, v8, v9
	v_pk_add_f32 v[4:5], v[4:5], v[2:3] neg_lo:[0,1] neg_hi:[0,1]
	v_or_b32_e32 v16, 48, v66
	v_max3_f32 v1, v1, v4, v5
	ds_bpermute_b32 v17, v120, v1
	v_lshl_add_u64 v[60:61], s[62:63], 0, v[80:81]
	v_lshl_add_u64 v[62:63], s[16:17], 0, v[80:81]
	v_lshl_add_u64 v[64:65], s[18:19], 0, v[80:81]
	s_waitcnt lgkmcnt(0)
	v_max_f32_e32 v17, v17, v17
	v_max_f32_e32 v17, v1, v17
	v_cndmask_b32_e32 v1, v17, v1, vcc
	ds_bpermute_b32 v18, v83, v1
	v_mov_b32_e32 v17, v67
	v_lshl_add_u64 v[80:81], s[62:63], 0, v[16:17]
	v_lshl_add_u64 v[82:83], s[16:17], 0, v[16:17]
	v_lshl_add_u64 v[100:101], s[18:19], 0, v[16:17]
	s_waitcnt lgkmcnt(0)
	v_max_f32_e32 v16, v18, v18
	v_max_f32_e32 v16, v1, v16
	v_cndmask_b32_e64 v1, v16, v1, s[0:1]
	ds_bpermute_b32 v18, v102, v1
	v_or_b32_e32 v16, 64, v66
	v_lshl_add_u64 v[102:103], s[62:63], 0, v[16:17]
	v_lshl_add_u64 v[104:105], s[16:17], 0, v[16:17]
	s_mov_b32 s0, 0x3fb8aa3b
	s_waitcnt lgkmcnt(0)
	v_max_f32_e32 v18, v18, v18
	v_max_f32_e32 v18, v1, v18
	v_cndmask_b32_e64 v1, v18, v1, s[2:3]
	ds_bpermute_b32 v18, v106, v1
	v_lshl_add_u64 v[106:107], s[18:19], 0, v[16:17]
	v_or_b32_e32 v16, 0x50, v66
	v_lshl_add_u64 v[108:109], s[62:63], 0, v[16:17]
	v_lshl_add_u64 v[112:113], s[18:19], 0, v[16:17]
	s_waitcnt lgkmcnt(0)
	v_max_f32_e32 v18, v18, v18
	v_max_f32_e32 v18, v1, v18
	v_cndmask_b32_e64 v1, v18, v1, s[4:5]
	ds_bpermute_b32 v18, v110, v1
	v_lshl_add_u64 v[110:111], s[16:17], 0, v[16:17]
	v_or_b32_e32 v16, 0x60, v66
	v_lshl_add_u64 v[116:117], s[16:17], 0, v[16:17]
	v_lshl_add_u64 v[118:119], s[18:19], 0, v[16:17]
	s_waitcnt lgkmcnt(0)
	v_max_f32_e32 v18, v18, v18
	v_max_f32_e32 v18, v1, v18
	v_cndmask_b32_e64 v1, v18, v1, s[8:9]
	ds_bpermute_b32 v18, v114, v1
	v_lshl_add_u64 v[114:115], s[62:63], 0, v[16:17]
	v_max_f32_e32 v16, v1, v1
	v_or_b32_e32 v66, 0x70, v66
	v_lshl_add_u64 v[122:123], s[16:17], 0, v[66:67]
	s_waitcnt lgkmcnt(0)
	v_max_f32_e32 v17, v18, v18
	v_max_f32_e32 v16, v16, v17
	v_cndmask_b32_e64 v1, v16, v1, s[10:11]
	ds_bpermute_b32 v1, v120, v1
	v_pk_mul_f32 v[16:17], v[32:33], s[0:1] op_sel_hi:[1,0]
	v_lshl_add_u64 v[120:121], s[62:63], 0, v[66:67]
	v_lshl_add_u64 v[66:67], s[18:19], 0, v[66:67]
	s_waitcnt lgkmcnt(0)
	v_max_f32_e32 v1, v1, v1
	v_max_f32_e32 v1, 0, v1
	v_cndmask_b32_e64 v1, v1, 0, vcc
	v_max_f32_e32 v18, v1, v32
	v_max_f32_e32 v19, v18, v33
	v_max_f32_e32 v32, v19, v26
	v_pk_mul_f32 v[20:21], v[18:19], s[0:1] op_sel_hi:[1,0]
	v_pk_add_f32 v[24:25], v[18:19], v[34:35]
	v_max_f32_e32 v33, v32, v27
	v_pk_mul_f32 v[18:19], v[26:27], s[0:1] op_sel_hi:[1,0]
	global_store_dwordx4 v[68:69], v[16:19], off
	v_pk_mul_f32 v[22:23], v[32:33], s[0:1] op_sel_hi:[1,0]
	v_pk_add_f32 v[26:27], v[32:33], v[36:37]
	v_max_f32_e32 v18, v33, v30
	v_max_f32_e32 v19, v18, v31
	v_pk_mul_f32 v[16:17], v[30:31], s[0:1] op_sel_hi:[1,0]
	v_max_f32_e32 v30, v19, v84
	global_store_dwordx4 v[70:71], v[20:23], off
	global_store_dwordx4 v[72:73], v[24:27], off
	v_max_f32_e32 v31, v30, v85
	v_pk_mul_f32 v[20:21], v[18:19], s[0:1] op_sel_hi:[1,0]
	v_pk_add_f32 v[24:25], v[18:19], v[38:39]
	v_pk_mul_f32 v[18:19], v[84:85], s[0:1] op_sel_hi:[1,0]
	global_store_dwordx4 v[76:77], v[16:19], off
	v_pk_mul_f32 v[22:23], v[30:31], s[0:1] op_sel_hi:[1,0]
	v_pk_add_f32 v[26:27], v[30:31], v[40:41]
	v_max_f32_e32 v18, v31, v28
	v_max_f32_e32 v19, v18, v29
	v_pk_mul_f32 v[16:17], v[28:29], s[0:1] op_sel_hi:[1,0]
	v_max_f32_e32 v28, v19, v86
	global_store_dwordx4 v[78:79], v[20:23], off
	global_store_dwordx4 v[74:75], v[24:27], off
	v_max_f32_e32 v29, v28, v87
	v_pk_mul_f32 v[20:21], v[18:19], s[0:1] op_sel_hi:[1,0]
	v_pk_add_f32 v[24:25], v[18:19], v[42:43]
	v_pk_mul_f32 v[18:19], v[86:87], s[0:1] op_sel_hi:[1,0]
	global_store_dwordx4 v[60:61], v[16:19], off
	v_pk_mul_f32 v[22:23], v[28:29], s[0:1] op_sel_hi:[1,0]
	v_pk_add_f32 v[26:27], v[28:29], v[44:45]
	v_max_f32_e32 v18, v29, v88
	v_max_f32_e32 v19, v18, v89
	v_max_f32_e32 v28, v19, v90
	global_store_dwordx4 v[62:63], v[20:23], off
	global_store_dwordx4 v[64:65], v[24:27], off
	v_pk_mul_f32 v[16:17], v[88:89], s[0:1] op_sel_hi:[1,0]
	v_pk_mul_f32 v[20:21], v[18:19], s[0:1] op_sel_hi:[1,0]
	v_pk_add_f32 v[24:25], v[18:19], v[46:47]
	v_max_f32_e32 v29, v28, v91
	v_pk_mul_f32 v[18:19], v[90:91], s[0:1] op_sel_hi:[1,0]
	global_store_dwordx4 v[80:81], v[16:19], off
	v_pk_mul_f32 v[22:23], v[28:29], s[0:1] op_sel_hi:[1,0]
	v_pk_add_f32 v[26:27], v[28:29], v[48:49]
	v_max_f32_e32 v18, v29, v92
	v_max_f32_e32 v19, v18, v93
	v_max_f32_e32 v28, v19, v94
	global_store_dwordx4 v[82:83], v[20:23], off
	global_store_dwordx4 v[100:101], v[24:27], off
	v_pk_mul_f32 v[16:17], v[92:93], s[0:1] op_sel_hi:[1,0]
	v_pk_mul_f32 v[20:21], v[18:19], s[0:1] op_sel_hi:[1,0]
	v_pk_add_f32 v[24:25], v[18:19], v[50:51]
	v_max_f32_e32 v29, v28, v95
	v_pk_mul_f32 v[18:19], v[94:95], s[0:1] op_sel_hi:[1,0]
	global_store_dwordx4 v[102:103], v[16:19], off
	v_pk_mul_f32 v[22:23], v[28:29], s[0:1] op_sel_hi:[1,0]
	v_pk_add_f32 v[26:27], v[28:29], v[52:53]
	v_max_f32_e32 v18, v29, v96
	v_max_f32_e32 v19, v18, v97
	v_max_f32_e32 v28, v19, v98
	global_store_dwordx4 v[104:105], v[20:23], off
	global_store_dwordx4 v[106:107], v[24:27], off
	v_pk_mul_f32 v[16:17], v[96:97], s[0:1] op_sel_hi:[1,0]
	v_pk_mul_f32 v[20:21], v[18:19], s[0:1] op_sel_hi:[1,0]
	v_pk_add_f32 v[24:25], v[18:19], v[54:55]
	v_max_f32_e32 v29, v28, v99
	v_pk_mul_f32 v[18:19], v[98:99], s[0:1] op_sel_hi:[1,0]
	global_store_dwordx4 v[108:109], v[16:19], off
	v_pk_add_f32 v[26:27], v[28:29], v[56:57]
	v_pk_mul_f32 v[22:23], v[28:29], s[0:1] op_sel_hi:[1,0]
	v_max_f32_e32 v18, v29, v58
	v_max_f32_e32 v19, v18, v59
	global_store_dwordx4 v[112:113], v[24:27], off
	global_store_dwordx4 v[110:111], v[20:23], off
	v_pk_mul_f32 v[16:17], v[58:59], s[0:1] op_sel_hi:[1,0]
	v_max_f32_e32 v24, v19, v12
	v_pk_mul_f32 v[20:21], v[18:19], s[0:1] op_sel_hi:[1,0]
	v_pk_add_f32 v[14:15], v[18:19], v[14:15]
	v_max_f32_e32 v25, v24, v13
	v_pk_mul_f32 v[18:19], v[12:13], s[0:1] op_sel_hi:[1,0]
	global_store_dwordx4 v[114:115], v[16:19], off
	v_pk_mul_f32 v[22:23], v[24:25], s[0:1] op_sel_hi:[1,0]
	global_store_dwordx4 v[116:117], v[20:23], off
	v_pk_add_f32 v[16:17], v[24:25], v[10:11]
	v_max_f32_e32 v10, v25, v8
	v_max_f32_e32 v11, v10, v9
	global_store_dwordx4 v[118:119], v[14:17], off
	v_pk_mul_f32 v[8:9], v[8:9], s[0:1] op_sel_hi:[1,0]
	v_pk_mul_f32 v[12:13], v[10:11], s[0:1] op_sel_hi:[1,0]
	v_max_f32_e32 v16, v11, v4
	v_pk_add_f32 v[6:7], v[10:11], v[6:7]
	v_max_f32_e32 v17, v16, v5
	v_pk_mul_f32 v[10:11], v[4:5], s[0:1] op_sel_hi:[1,0]
	global_store_dwordx4 v[120:121], v[8:11], off
	v_pk_mul_f32 v[14:15], v[16:17], s[0:1] op_sel_hi:[1,0]
	global_store_dwordx4 v[122:123], v[12:15], off
	v_pk_add_f32 v[8:9], v[16:17], v[2:3]
	global_store_dwordx4 v[66:67], v[6:9], off

.LBB0_417:
	s_or_b64 exec, exec, s[10:11]
	s_waitcnt lgkmcnt(0)
	ds_read2st64_b32 v[2:3], v97 offset1:1
	v_lshl_add_u64 v[4:5], s[0:1], 1, v[64:65]
	global_load_ushort v6, v[4:5], off
	global_load_ushort v7, v[4:5], off offset:128
	global_load_dword v8, v[66:67], off
	global_load_dword v9, v[66:67], off offset:256
	s_mov_b32 s8, 0xf800000
	s_waitcnt lgkmcnt(0)
	v_add_f32_e32 v4, v2, v3
	ds_bpermute_b32 v5, v91, v4
	s_lshl_b64 s[0:1], s[74:75], 11
	v_lshl_add_u64 v[72:73], v[72:73], 0, s[20:21]
	v_lshl_add_u64 v[74:75], v[74:75], 0, s[20:21]
	s_waitcnt lgkmcnt(0)
	v_add_f32_e32 v4, v4, v5
	ds_bpermute_b32 v5, v92, v4
	s_waitcnt lgkmcnt(0)
	v_add_f32_e32 v4, v4, v5
	ds_bpermute_b32 v5, v93, v4
	s_waitcnt lgkmcnt(0)
	v_add_f32_e32 v4, v4, v5
	ds_bpermute_b32 v5, v94, v4
	s_waitcnt lgkmcnt(0)
	v_add_f32_e32 v4, v4, v5
	ds_bpermute_b32 v5, v95, v4
	s_waitcnt lgkmcnt(0)
	v_add_f32_e32 v4, v4, v5
	ds_bpermute_b32 v5, v96, v4
	s_waitcnt lgkmcnt(0)
	v_add_f32_e32 v4, v4, v5
	v_fmac_f32_e32 v3, 0xbc000000, v4
	v_fmamk_f32 v2, v4, 0xbc000000, v2
	v_mul_f32_e32 v4, v3, v3
	v_fmac_f32_e32 v4, v2, v2
	ds_bpermute_b32 v5, v91, v4
	s_waitcnt lgkmcnt(0)
	v_add_f32_e32 v4, v4, v5
	ds_bpermute_b32 v5, v92, v4
	s_waitcnt lgkmcnt(0)
	v_add_f32_e32 v4, v4, v5
	ds_bpermute_b32 v5, v93, v4
	s_waitcnt lgkmcnt(0)
	v_add_f32_e32 v4, v4, v5
	ds_bpermute_b32 v5, v94, v4
	s_waitcnt lgkmcnt(0)
	v_add_f32_e32 v4, v4, v5
	ds_bpermute_b32 v5, v95, v4
	s_waitcnt lgkmcnt(0)
	v_add_f32_e32 v10, v4, v5
	ds_bpermute_b32 v11, v96, v10
	v_lshl_add_u64 v[4:5], v[68:69], 0, s[0:1]
	s_waitcnt vmcnt(3)
	v_lshlrev_b32_e32 v6, 16, v6
	s_waitcnt lgkmcnt(0)
	v_add_f32_e32 v10, v10, v11
	v_fmamk_f32 v10, v10, 0x3c000000, v101
	v_mul_f32_e32 v11, 0x4f800000, v10
	v_cmp_gt_f32_e32 vcc, s8, v10
	s_waitcnt vmcnt(2)
	v_lshlrev_b32_e32 v7, 16, v7
	v_mul_f32_e32 v6, 0xbfb8aa3b, v6
	v_cndmask_b32_e32 v10, v10, v11, vcc
	v_sqrt_f32_e32 v11, v10
	v_mul_f32_e32 v7, 0xbfb8aa3b, v7
	v_exp_f32_e32 v6, v6
	v_exp_f32_e32 v7, v7
	v_add_u32_e32 v16, -1, v11
	v_add_u32_e32 v17, 1, v11
	v_add_f32_e32 v6, 1.0, v6
	v_fma_f32 v20, -v16, v11, v10
	v_add_f32_e32 v7, 1.0, v7
	v_div_scale_f32 v12, s[0:1], v6, v6, 1.0
	v_fma_f32 v21, -v17, v11, v10
	v_cmp_ge_f32_e64 s[10:11], 0, v20
	v_div_scale_f32 v14, s[8:9], v7, v7, 1.0
	v_rcp_f32_e32 v18, v12
	v_cndmask_b32_e64 v11, v11, v16, s[10:11]
	v_cmp_lt_f32_e64 s[10:11], 0, v21
	v_rcp_f32_e32 v19, v14
	v_div_scale_f32 v13, s[0:1], 1.0, v6, 1.0
	v_cndmask_b32_e64 v11, v11, v17, s[10:11]
	v_mul_f32_e32 v16, 0x37800000, v11
	v_cndmask_b32_e32 v11, v11, v16, vcc
	v_cmp_class_f32_e32 vcc, v10, v102
	v_fma_f32 v17, -v12, v18, 1.0
	v_fma_f32 v20, -v14, v19, 1.0
	v_cndmask_b32_e32 v10, v11, v10, vcc
	v_fmac_f32_e32 v18, v17, v18
	v_div_scale_f32 v17, s[10:11], v10, v10, 1.0
	v_div_scale_f32 v15, s[8:9], 1.0, v7, 1.0
	v_fmac_f32_e32 v19, v20, v19
	v_rcp_f32_e32 v23, v17
	v_mul_f32_e32 v11, v13, v18
	v_mul_f32_e32 v16, v15, v19
	v_fma_f32 v21, -v12, v11, v13
	v_fma_f32 v22, -v14, v16, v15
	v_fmac_f32_e32 v11, v21, v18
	v_fmac_f32_e32 v16, v22, v19
	v_fma_f32 v12, -v12, v11, v13
	v_fma_f32 v13, -v14, v16, v15
	v_fma_f32 v14, -v17, v23, 1.0
	v_div_scale_f32 v20, vcc, 1.0, v10, 1.0
	v_fmac_f32_e32 v23, v14, v23
	v_mul_f32_e32 v14, v20, v23
	v_fma_f32 v15, -v17, v14, v20
	v_fmac_f32_e32 v14, v15, v23
	v_fma_f32 v15, -v17, v14, v20
	v_div_fmas_f32 v14, v15, v23, v14
	v_div_fixup_f32 v10, v14, v10, 1.0
	s_mov_b64 vcc, s[0:1]
	v_div_fmas_f32 v11, v12, v18, v11
	v_mul_f32_e32 v2, v2, v10
	s_mov_b64 vcc, s[8:9]
	v_div_fixup_f32 v6, v11, v6, 1.0
	v_mul_f32_e32 v3, v3, v10
	v_div_fmas_f32 v10, v13, v19, v16
	s_waitcnt vmcnt(1)
	v_mul_f32_e32 v2, v8, v2
	s_waitcnt vmcnt(0)
	v_mul_f32_e32 v3, v9, v3
	v_div_fixup_f32 v7, v10, v7, 1.0
	v_mul_f32_e32 v2, v6, v2
	v_mul_f32_e32 v3, v7, v3
	v_bfe_u32 v6, v2, 16, 1
	v_bfe_u32 v7, v3, 16, 1
	v_add3_u32 v2, v2, v6, s24
	global_store_short_d16_hi v[4:5], v2, off offset:1024
	v_add3_u32 v2, v3, v7, s24
	global_store_short_d16_hi v[4:5], v2, off offset:1152
	s_waitcnt lgkmcnt(0)
	s_add_i32 s8, s78, 0x100
	s_cmpk_lt_u32 s78, 0x100
	s_branch .LBB0_454
